# DMA version + first 16 V transpose-reads hoisted above the DMA issue block
# baseline (speedup 1.0000x reference)
.LBB0_400:
	v_cvt_pk_bf16_f32 v182, v148, v149
	v_cvt_pk_bf16_f32 v183, v152, v153
	v_cvt_pk_bf16_f32 v184, v154, v155
	v_cvt_pk_bf16_f32 v185, v158, v159
	v_cvt_pk_bf16_f32 v160, v150, v151
	v_cvt_pk_bf16_f32 v161, v156, v157
	v_cvt_pk_bf16_f32 v162, v162, v163
	v_cvt_pk_bf16_f32 v163, v166, v167
	ds_read_b64_tr_b16 v[186:187], v203 offset:0
	ds_read_b64_tr_b16 v[188:189], v203 offset:0x800
	ds_read_b64_tr_b16 v[214:215], v203 offset:0x200
	ds_read_b64_tr_b16 v[216:217], v203 offset:0xa00
	ds_read_b64_tr_b16 v[218:219], v203 offset:0x400
	ds_read_b64_tr_b16 v[220:221], v203 offset:0xc00
	ds_read_b64_tr_b16 v[222:223], v203 offset:0x600
	ds_read_b64_tr_b16 v[224:225], v203 offset:0xe00
	ds_read_b64_tr_b16 v[226:227], v203 offset:0x1000
	ds_read_b64_tr_b16 v[228:229], v203 offset:0x1800
	ds_read_b64_tr_b16 v[230:231], v203 offset:0x1200
	ds_read_b64_tr_b16 v[232:233], v203 offset:0x1a00
	ds_read_b64_tr_b16 v[234:235], v203 offset:0x1400
	ds_read_b64_tr_b16 v[236:237], v203 offset:0x1c00
	ds_read_b64_tr_b16 v[238:239], v203 offset:0x1600
	ds_read_b64_tr_b16 v[240:241], v203 offset:0x1e00
	s_cmpk_lt_u32 s51, 0x100
	s_cselect_b32 s0, s38, s34
	s_add_i32 s3, s0, s51
	s_mul_i32 s0, s3, 0x1800
	s_mul_hi_i32 s1, s3, 0x1800
	s_add_u32 s0, s39, s0
	s_addc_u32 s1, s42, s1
	s_max_i32 vcc_lo, s100, 0
	s_add_i32 vcc_lo, vcc_lo, s96
	s_add_i32 m0, vcc_lo, 0x4100
	s_nop 0
	global_load_lds_dwordx4 v129, s[0:1]
	s_add_i32 m0, vcc_lo, 0x4500
	s_nop 0
	global_load_lds_dwordx4 v130, s[0:1]
	s_mul_i32 s0, s3, 0x1800
	s_mul_hi_i32 s1, s3, 0x1800
	s_add_u32 s0, s28, s0
	s_addc_u32 s1, s29, s1
	s_max_i32 vcc_lo, s101, 0
	s_add_i32 vcc_lo, vcc_lo, s97
	s_add_i32 m0, vcc_lo, 0xa100
	s_nop 0
	global_load_lds_dwordx4 v128, s[0:1]
	s_nop 0
	s_waitcnt lgkmcnt(8)
	v_exp_f32_e32 v112, v112
	v_mfma_f32_32x32x16_bf16 v[0:15], v[144:147], v[186:189], v[0:15]
	v_exp_f32_e32 v113, v113
	v_exp_f32_e32 v114, v114
	v_exp_f32_e32 v115, v115
	v_exp_f32_e32 v116, v116
	v_exp_f32_e32 v117, v117
	v_exp_f32_e32 v118, v118
	v_exp_f32_e32 v119, v119
	v_mfma_f32_32x32x16_bf16 v[48:63], v[144:147], v[214:217], v[48:63]
	v_exp_f32_e32 v120, v120
	v_exp_f32_e32 v121, v121
	v_exp_f32_e32 v122, v122
	v_exp_f32_e32 v123, v123
	v_exp_f32_e32 v124, v124
	v_exp_f32_e32 v125, v125
	v_exp_f32_e32 v126, v126
	v_mfma_f32_32x32x16_bf16 v[32:47], v[144:147], v[218:221], v[32:47]
	v_exp_f32_e32 v127, v127
	v_mfma_f32_32x32x16_bf16 v[16:31], v[144:147], v[222:225], v[16:31]
	ds_read_b64_tr_b16 v[144:145], v203 offset:0x2000
	ds_read_b64_tr_b16 v[146:147], v203 offset:0x2800
	ds_read_b64_tr_b16 v[186:187], v203 offset:0x2200
	ds_read_b64_tr_b16 v[188:189], v203 offset:0x2a00
	ds_read_b64_tr_b16 v[214:215], v203 offset:0x2400
	ds_read_b64_tr_b16 v[216:217], v203 offset:0x2c00
	ds_read_b64_tr_b16 v[218:219], v203 offset:0x2600
	ds_read_b64_tr_b16 v[220:221], v203 offset:0x2e00
	s_waitcnt lgkmcnt(8)
	ds_read_b64_tr_b16 v[222:223], v203 offset:0x3000
	ds_read_b64_tr_b16 v[224:225], v203 offset:0x3800
	s_nop 0
	v_mfma_f32_32x32x16_bf16 v[0:15], v[140:143], v[226:229], v[0:15]
	ds_read_b64_tr_b16 v[226:227], v203 offset:0x3200
	ds_read_b64_tr_b16 v[228:229], v203 offset:0x3a00
	v_mfma_f32_32x32x16_bf16 v[48:63], v[140:143], v[230:233], v[48:63]
	ds_read_b64_tr_b16 v[230:231], v203 offset:0x3400
	ds_read_b64_tr_b16 v[232:233], v203 offset:0x3c00
	v_mfma_f32_32x32x16_bf16 v[32:47], v[140:143], v[234:237], v[32:47]
	ds_read_b64_tr_b16 v[234:235], v203 offset:0x3600
	ds_read_b64_tr_b16 v[236:237], v203 offset:0x3e00
	s_waitcnt lgkmcnt(8)
	s_nop 0
	s_waitcnt lgkmcnt(0)
	v_mfma_f32_32x32x16_bf16 v[16:31], v[140:143], v[238:241], v[16:31]
	v_add_f32_e32 v140, 0, v112
	v_add_f32_e32 v140, v113, v140
	v_add_f32_e32 v140, v114, v140
	v_add_f32_e32 v140, v115, v140
	v_add_f32_e32 v140, v116, v140
	v_add_f32_e32 v140, v117, v140
	v_add_f32_e32 v140, v118, v140
	v_mfma_f32_32x32x16_bf16 v[0:15], v[182:185], v[144:147], v[0:15]
	v_add_f32_e32 v140, v119, v140
	v_add_f32_e32 v140, v120, v140
	v_add_f32_e32 v140, v121, v140
	v_add_f32_e32 v140, v122, v140
	v_add_f32_e32 v140, v123, v140
	v_add_f32_e32 v140, v124, v140
	v_add_f32_e32 v140, v125, v140
	v_mfma_f32_32x32x16_bf16 v[48:63], v[182:185], v[186:189], v[48:63]
	v_add_f32_e32 v140, v126, v140
	v_add_f32_e32 v165, v127, v140
	v_cvt_pk_bf16_f32 v144, v112, v113
	v_cvt_pk_bf16_f32 v145, v114, v115
	v_cvt_pk_bf16_f32 v146, v116, v117
	v_cvt_pk_bf16_f32 v147, v118, v119
	v_cvt_pk_bf16_f32 v140, v120, v121
	v_mfma_f32_32x32x16_bf16 v[32:47], v[182:185], v[214:217], v[32:47]
	v_cvt_pk_bf16_f32 v141, v122, v123
	v_cvt_pk_bf16_f32 v142, v124, v125
	v_cvt_pk_bf16_f32 v143, v126, v127
	v_mfma_f32_32x32x16_bf16 v[16:31], v[182:185], v[218:221], v[16:31]
	s_waitcnt vmcnt(3)
	s_waitcnt lgkmcnt(0)
	s_barrier
	v_mfma_f32_32x32x16_bf16 v[0:15], v[160:163], v[222:225], v[0:15]
	v_mfma_f32_32x32x16_bf16 v[48:63], v[160:163], v[226:229], v[48:63]
	v_mfma_f32_32x32x16_bf16 v[32:47], v[160:163], v[230:233], v[32:47]
	v_mfma_f32_32x32x16_bf16 v[16:31], v[160:163], v[234:237], v[16:31]
	v_add_u32_e32 v208, s101, v208
	v_add_u32_e32 v209, s101, v209
	v_add_u32_e32 v210, s101, v210
	v_add_u32_e32 v211, s101, v211
	ds_read_b128 v[160:163], v208 offset:32768
	ds_read_b128 v[222:225], v208 offset:36864
	v_exp_f32_e32 v166, v84
	v_exp_f32_e32 v167, v85
	s_waitcnt lgkmcnt(1)
	v_mfma_f32_32x32x16_bf16 v[112:127], v[160:163], v[64:67], v[96:111]
	ds_read_b128 v[160:163], v209 offset:32768
	ds_read_b128 v[226:229], v209 offset:36864
	ds_read_b128 v[238:241], v210 offset:36864
	ds_read_b128 v[182:185], v210 offset:32768
	ds_read_b128 v[242:245], v211 offset:36864
	ds_read_b128 v[188:191], v211 offset:32768
	v_exp_f32_e32 v186, v90
	v_exp_f32_e32 v187, v91
	s_andn2_b64 s[0:1], s[6:7], exec
	s_and_b64 s[6:7], s[8:9], exec
	s_or_b64 s[6:7], s[0:1], s[6:7]
	s_waitcnt lgkmcnt(5)
	v_mfma_f32_32x32x16_bf16 v[112:127], v[160:163], v[68:71], v[112:127]
	v_exp_f32_e32 v160, v80
	v_exp_f32_e32 v161, v81
	v_exp_f32_e32 v162, v82
	v_exp_f32_e32 v163, v83
	v_add_f32_e32 v80, v160, v165
	v_add_f32_e32 v80, v161, v80
	v_add_f32_e32 v165, v162, v80
	s_waitcnt lgkmcnt(2)
	v_mfma_f32_32x32x16_bf16 v[112:127], v[182:185], v[72:75], v[112:127]
	v_exp_f32_e32 v182, v86
	v_exp_f32_e32 v183, v87
	v_exp_f32_e32 v184, v88
	v_exp_f32_e32 v185, v89
	v_add_f32_e32 v165, v163, v165
	v_add_f32_e32 v165, v166, v165
	v_add_f32_e32 v165, v167, v165
	s_waitcnt lgkmcnt(0)
	v_mfma_f32_32x32x16_bf16 v[112:127], v[188:191], v[76:79], v[112:127]
	v_exp_f32_e32 v188, v92
	v_exp_f32_e32 v189, v93
	v_exp_f32_e32 v190, v94
	v_exp_f32_e32 v191, v95
	v_add_f32_e32 v165, v182, v165
	v_add_f32_e32 v165, v183, v165
	v_add_f32_e32 v165, v184, v165
	v_mfma_f32_32x32x16_bf16 v[80:95], v[222:225], v[64:67], v[96:111]
	v_add_f32_e32 v165, v185, v165
	v_add_f32_e32 v165, v186, v165
	v_add_f32_e32 v165, v187, v165
	v_add_f32_e32 v165, v188, v165
	v_add_f32_e32 v165, v189, v165
	v_add_f32_e32 v165, v190, v165
	v_add_f32_e32 v165, v191, v165
	v_mfma_f32_32x32x16_bf16 v[80:95], v[226:229], v[68:71], v[80:95]
	v_mov_b32_e32 v179, v165
	s_nop 1
	v_permlane32_swap_b32_e32 v165, v179
	v_add_f32_e64 v178, v164, v178
	v_add_f32_e64 v179, v165, v179
	v_cmp_ge_f32_e32 vcc, s99, v179
	s_cmp_eq_u64 vcc, exec
	v_mfma_f32_32x32x16_bf16 v[80:95], v[238:241], v[72:75], v[80:95]
	v_mfma_f32_32x32x16_bf16 v[80:95], v[242:245], v[76:79], v[80:95]
	s_cbranch_scc0 .LBB0_408
.LBB0_401:
	v_cvt_pk_bf16_f32 v164, v160, v161
	v_cvt_pk_bf16_f32 v165, v162, v163
	v_cvt_pk_bf16_f32 v166, v166, v167
	v_cvt_pk_bf16_f32 v167, v182, v183
	v_cvt_pk_bf16_f32 v160, v184, v185
	v_cvt_pk_bf16_f32 v161, v186, v187
	v_cvt_pk_bf16_f32 v162, v188, v189
	v_cvt_pk_bf16_f32 v163, v190, v191
	ds_read_b64_tr_b16 v[182:183], v202 offset:0
	ds_read_b64_tr_b16 v[184:185], v202 offset:0x800
	ds_read_b64_tr_b16 v[186:187], v202 offset:0x200
	ds_read_b64_tr_b16 v[188:189], v202 offset:0xa00
	ds_read_b64_tr_b16 v[214:215], v202 offset:0x400
	ds_read_b64_tr_b16 v[216:217], v202 offset:0xc00
	ds_read_b64_tr_b16 v[218:219], v202 offset:0x600
	ds_read_b64_tr_b16 v[220:221], v202 offset:0xe00
	ds_read_b64_tr_b16 v[222:223], v202 offset:0x1000
	ds_read_b64_tr_b16 v[224:225], v202 offset:0x1800
	ds_read_b64_tr_b16 v[226:227], v202 offset:0x1200
	ds_read_b64_tr_b16 v[228:229], v202 offset:0x1a00
	ds_read_b64_tr_b16 v[230:231], v202 offset:0x1400
	ds_read_b64_tr_b16 v[232:233], v202 offset:0x1c00
	ds_read_b64_tr_b16 v[234:235], v202 offset:0x1600
	ds_read_b64_tr_b16 v[236:237], v202 offset:0x1e00
	s_cmp_ge_u32 s50, s35
	s_cselect_b64 s[8:9], -1, 0
	s_and_b64 vcc, exec, s[8:9]
	s_cbranch_vccnz .LBB0_403
	s_add_i32 s0, s34, s51
	s_add_i32 s3, s0, 64
	s_mul_i32 s0, s3, 0x1800
	s_mul_hi_i32 s1, s3, 0x1800
	s_add_u32 s0, s39, s0
	s_addc_u32 s1, s42, s1
	s_sub_i32 vcc_lo, 0, s100
	s_max_i32 vcc_lo, vcc_lo, 0
	s_add_i32 vcc_lo, vcc_lo, s96
	s_add_i32 m0, vcc_lo, 0x100
	s_nop 0
	global_load_lds_dwordx4 v129, s[0:1]
	s_add_i32 m0, vcc_lo, 0x500
	s_nop 0
	global_load_lds_dwordx4 v130, s[0:1]
	s_mul_i32 s0, s3, 0x1800
	s_mul_hi_i32 s1, s3, 0x1800
	s_add_u32 s0, s28, s0
	s_addc_u32 s1, s29, s1
	s_sub_i32 vcc_lo, 0, s101
	s_max_i32 vcc_lo, vcc_lo, 0
	s_add_i32 vcc_lo, vcc_lo, s97
	s_add_i32 m0, vcc_lo, 0x8100
	s_nop 0
	global_load_lds_dwordx4 v128, s[0:1]
.LBB0_403:
	v_add_f32_e32 v178, v179, v178
	s_nop 0
	s_waitcnt lgkmcnt(8)
	v_exp_f32_e32 v112, v112
	v_mfma_f32_32x32x16_bf16 v[0:15], v[144:147], v[182:185], v[0:15]
	v_exp_f32_e32 v113, v113
	v_exp_f32_e32 v114, v114
	v_exp_f32_e32 v115, v115
	v_exp_f32_e32 v116, v116
	v_exp_f32_e32 v117, v117
	v_exp_f32_e32 v118, v118
	v_exp_f32_e32 v119, v119
	v_mfma_f32_32x32x16_bf16 v[48:63], v[144:147], v[186:189], v[48:63]
	v_exp_f32_e32 v120, v120
	v_exp_f32_e32 v121, v121
	v_exp_f32_e32 v122, v122
	v_exp_f32_e32 v123, v123
	v_exp_f32_e32 v124, v124
	v_exp_f32_e32 v125, v125
	v_exp_f32_e32 v126, v126
	v_mfma_f32_32x32x16_bf16 v[32:47], v[144:147], v[214:217], v[32:47]
	v_exp_f32_e32 v127, v127
	s_addk_i32 s51, 0x80
	s_add_i32 s50, s50, 2
	s_and_b64 vcc, exec, s[8:9]
	v_mfma_f32_32x32x16_bf16 v[16:31], v[144:147], v[218:221], v[16:31]
	ds_read_b64_tr_b16 v[144:145], v202 offset:0x2000
	ds_read_b64_tr_b16 v[146:147], v202 offset:0x2800
	ds_read_b64_tr_b16 v[182:183], v202 offset:0x2200
	ds_read_b64_tr_b16 v[184:185], v202 offset:0x2a00
	ds_read_b64_tr_b16 v[186:187], v202 offset:0x2400
	ds_read_b64_tr_b16 v[188:189], v202 offset:0x2c00
	ds_read_b64_tr_b16 v[214:215], v202 offset:0x2600
	ds_read_b64_tr_b16 v[216:217], v202 offset:0x2e00
	s_waitcnt lgkmcnt(8)
	ds_read_b64_tr_b16 v[218:219], v202 offset:0x3000
	ds_read_b64_tr_b16 v[220:221], v202 offset:0x3800
	s_nop 0
	v_mfma_f32_32x32x16_bf16 v[0:15], v[140:143], v[222:225], v[0:15]
	ds_read_b64_tr_b16 v[222:223], v202 offset:0x3200
	ds_read_b64_tr_b16 v[224:225], v202 offset:0x3a00
	v_mfma_f32_32x32x16_bf16 v[48:63], v[140:143], v[226:229], v[48:63]
	ds_read_b64_tr_b16 v[226:227], v202 offset:0x3400
	ds_read_b64_tr_b16 v[228:229], v202 offset:0x3c00
	v_mfma_f32_32x32x16_bf16 v[32:47], v[140:143], v[230:233], v[32:47]
	ds_read_b64_tr_b16 v[230:231], v202 offset:0x3600
	ds_read_b64_tr_b16 v[232:233], v202 offset:0x3e00
	s_waitcnt lgkmcnt(8)
	s_nop 0
	s_waitcnt lgkmcnt(0)
	v_mfma_f32_32x32x16_bf16 v[16:31], v[140:143], v[234:237], v[16:31]
	v_add_f32_e32 v140, 0, v112
	v_add_f32_e32 v140, v113, v140
	v_add_f32_e32 v140, v114, v140
	v_add_f32_e32 v140, v115, v140
	v_add_f32_e32 v140, v116, v140
	v_add_f32_e32 v140, v117, v140
	v_add_f32_e32 v140, v118, v140
	v_mfma_f32_32x32x16_bf16 v[0:15], v[164:167], v[144:147], v[0:15]
	v_add_f32_e32 v140, v119, v140
	v_add_f32_e32 v140, v120, v140
	v_add_f32_e32 v140, v121, v140
	v_add_f32_e32 v140, v122, v140
	v_add_f32_e32 v140, v123, v140
	v_add_f32_e32 v140, v124, v140
	v_add_f32_e32 v140, v125, v140
	v_mfma_f32_32x32x16_bf16 v[48:63], v[164:167], v[182:185], v[48:63]
	v_add_f32_e32 v140, v126, v140
	v_cvt_pk_bf16_f32 v144, v112, v113
	v_cvt_pk_bf16_f32 v145, v114, v115
	v_cvt_pk_bf16_f32 v146, v116, v117
	v_cvt_pk_bf16_f32 v147, v118, v119
	v_mfma_f32_32x32x16_bf16 v[32:47], v[164:167], v[186:189], v[32:47]
	v_mfma_f32_32x32x16_bf16 v[16:31], v[164:167], v[214:217], v[16:31]
	v_add_f32_e32 v164, v127, v140
	v_cvt_pk_bf16_f32 v140, v120, v121
	v_cvt_pk_bf16_f32 v141, v122, v123
	v_cvt_pk_bf16_f32 v142, v124, v125
	v_cvt_pk_bf16_f32 v143, v126, v127
	v_mfma_f32_32x32x16_bf16 v[0:15], v[160:163], v[218:221], v[0:15]
	s_waitcnt vmcnt(3)
	s_cbranch_vccz .Ldma_w3
	s_waitcnt vmcnt(0)
